# attention first key tile: its 8 K fragment LDS reads issued together with counted waits instead of read-wait-MFMA eight times
# baseline (speedup 1.0000x reference)
; __device__ __forceinline__ void cmask(f32x16& p0, f32x16& p1, int jb, int qrel, int hi) {
;     const float NEG = -INFINITY; int kb = 64 * jb + 4 * hi;
; #pragma unroll
;     for (int r = 0; r < 16; ++r) { int kv = kb + (r & 3) + 8 * (r >> 2); if (kv > qrel) p0[r] = NEG; if (kv + 32 > qrel) p1[r] = NEG; }
; }
; __device__ __forceinline__ void mmask(f32x16& p0, f32x16& p1, bool keep) {
;     const float NEG = -INFINITY;
; #pragma unroll
;     for (int r = 0; r < 16; ++r) { p0[r] = keep ? p0[r] : NEG; p1[r] = keep ? p1[r] : NEG; }
; }
; __device__ __forceinline__ void glds16(const void* gsrc, unsigned lds_dst) { unsigned keep;
;     asm volatile("s_mov_b32 %0, m0\n\ts_mov_b32 m0, %2\n\ts_nop 0\n\tglobal_load_lds_dwordx4 %1, off\n\ts_mov_b32 m0, %0" : "=&s"(keep) : "v"(gsrc), "s"(lds_dst) : "memory"); }
; __device__ __forceinline__ float max3f(float a, float b, float c) { float r; asm("v_max3_f32 %0, %1, %2, %3" : "=v"(r) : "v"(a), "v"(b), "v"(c)); return r; }
; __device__ __forceinline__ float max2f(float a, float b) { float r; asm("v_max_f32_e32 %0, %1, %2" : "=v"(r) : "v"(a), "v"(b)); return r; }
; __device__ __forceinline__ float fadd_s(float a, float b) { float r; asm("v_add_f32_e32 %0, %1, %2" : "=v"(r) : "v"(a), "v"(b)); return r; }
; __device__ __forceinline__ float fsub_s(float a, float b) { float r; asm("v_sub_f32_e32 %0, %1, %2" : "=v"(r) : "v"(a), "v"(b)); return r; }
; __device__ __forceinline__ void qkt(f32x16& p0, f32x16& p1, const char* Kslot, const f16x8* qr, const f32x16& negm, int r32, int hi) {
;     const char* kb = Kslot + hi * 1024 + r32 * 16;
; #pragma unroll
;     for (int d0 = 0; d0 < 4; ++d0) {
;         const f16x8 b0 = *reinterpret_cast<const f16x8*>(kb + d0 * 2048);
;         const f16x8 b1 = *reinterpret_cast<const f16x8*>(kb + d0 * 2048 + 512);
;         if (d0 == 0) { p0 = __builtin_amdgcn_mfma_f32_32x32x16_f16(b0, qr[0], negm, 0, 0, 0); p1 = __builtin_amdgcn_mfma_f32_32x32x16_f16(b1, qr[0], negm, 0, 0, 0); }
;         else { p0 = __builtin_amdgcn_mfma_f32_32x32x16_f16(b0, qr[d0], p0, 0, 0, 0); p1 = __builtin_amdgcn_mfma_f32_32x32x16_f16(b1, qr[d0], p1, 0, 0, 0); } }
; }
.Lattn_q_loaded:
	v_and_b32_e32 v3, 1, v210
	v_cmp_eq_u32_e32 vcc, 0, v3
	s_and_b64 s[2:3], s[4:5], vcc
	s_cmp_lg_u32 0, -1
	v_mov_b32 v2, 0
	s_cselect_b32 s8, 0, 0
	v_cndmask_b32_e64 v18, v2, v200, s[2:3]
	v_mov_b32_e32 v19, v18
	v_mov_b32_e32 v20, v18
	v_mov_b32_e32 v21, v18
	v_mov_b32_e32 v22, v18
	v_mov_b32_e32 v23, v18
	v_mov_b32_e32 v24, v18
	v_mov_b32_e32 v25, v18
	v_mov_b32_e32 v26, v18
	v_mov_b32_e32 v27, v18
	v_mov_b32_e32 v28, v18
	v_mov_b32_e32 v29, v18
	v_mov_b32_e32 v30, v18
	v_mov_b32_e32 v31, v18
	v_mov_b32_e32 v32, v18
	v_mov_b32_e32 v33, v18
	s_waitcnt vmcnt(3) lgkmcnt(0)
	s_barrier
	s_waitcnt vmcnt(5)
	ds_read_b128 v[4:7], v211
	ds_read_b128 v[50:53], v211 offset:512
	ds_read_b128 v[54:57], v211 offset:2048
	ds_read_b128 v[58:61], v211 offset:2560
	ds_read_b128 v[62:65], v211 offset:4096
	ds_read_b128 v[66:69], v211 offset:4608
	ds_read_b128 v[70:73], v211 offset:6144
	ds_read_b128 v[74:77], v211 offset:6656
	s_cmp_lg_u32 s70, 0
	s_cselect_b64 s[8:9], -1, 0
	s_cmp_eq_u32 s70, 0
	s_cselect_b64 s[30:31], -1, 0
	s_cmp_lt_i32 s29, 2
	s_cselect_b64 s[52:53], -1, 0
	s_and_b64 s[30:31], s[30:31], s[52:53]
	s_andn2_b64 vcc, exec, s[30:31]
	v_lshlrev_b32_e32 v208, 2, v204
	s_waitcnt vmcnt(3) lgkmcnt(7)
	v_mfma_f32_32x32x16_f16 v[34:49], v[4:7], v[138:141], v[18:33]
	s_waitcnt lgkmcnt(6)
	v_mfma_f32_32x32x16_f16 v[18:33], v[50:53], v[138:141], v[18:33]
	s_waitcnt vmcnt(2) lgkmcnt(5)
	v_mfma_f32_32x32x16_f16 v[34:49], v[54:57], v[130:133], v[34:49]
	s_waitcnt lgkmcnt(4)
	v_mfma_f32_32x32x16_f16 v[18:33], v[58:61], v[130:133], v[18:33]
	s_waitcnt vmcnt(1) lgkmcnt(3)
	v_mfma_f32_32x32x16_f16 v[34:49], v[62:65], v[118:121], v[34:49]
	s_waitcnt lgkmcnt(2)
	v_mfma_f32_32x32x16_f16 v[18:33], v[66:69], v[118:121], v[18:33]
	s_waitcnt vmcnt(0) lgkmcnt(1)
	v_mfma_f32_32x32x16_f16 v[34:49], v[70:73], v[114:117], v[34:49]
	s_waitcnt lgkmcnt(0)
	v_mfma_f32_32x32x16_f16 v[18:33], v[74:77], v[114:117], v[18:33]
	s_nop 15
	s_nop 7
	s_cbranch_vccnz .LBB0_540
	v_mov_b32_e32 v3, v190
	v_or_b32_e32 v4, 32, v208
	v_add_u32_e32 v3, s89, v3
	v_cmp_le_i32_e32 vcc, v4, v3
	v_or_b32_e32 v4, 33, v208
	s_nop 5
	v_cndmask_b32_e32 v18, v200, v18, vcc
	v_cmp_lt_i32_e32 vcc, v208, v3
	s_nop 1
	v_cndmask_b32_e32 v35, v200, v35, vcc
	v_cmp_le_i32_e32 vcc, v208, v3
	s_nop 1
	v_cndmask_b32_e32 v34, v200, v34, vcc
	v_cmp_le_i32_e32 vcc, v4, v3
	v_or_b32_e32 v4, 2, v208
	s_nop 0
	v_cndmask_b32_e32 v19, v200, v19, vcc
	v_cmp_le_i32_e32 vcc, v4, v3
	v_or_b32_e32 v4, 34, v208
	s_nop 0
	v_cndmask_b32_e32 v36, v200, v36, vcc
	v_cmp_le_i32_e32 vcc, v4, v3
	v_or_b32_e32 v4, 3, v208
	s_nop 0
	v_cndmask_b32_e32 v20, v200, v20, vcc
	v_cmp_le_i32_e32 vcc, v4, v3
	v_or_b32_e32 v4, 35, v208
	s_nop 0
	v_cndmask_b32_e32 v37, v200, v37, vcc
	v_cmp_le_i32_e32 vcc, v4, v3
	v_or_b32_e32 v4, 8, v208
	s_nop 0
	v_cndmask_b32_e32 v21, v200, v21, vcc
	v_cmp_le_i32_e32 vcc, v4, v3
	v_or_b32_e32 v4, 40, v208
	s_nop 0
	v_cndmask_b32_e32 v38, v200, v38, vcc
	v_cmp_le_i32_e32 vcc, v4, v3
	v_or_b32_e32 v4, 9, v208
	s_nop 0
	v_cndmask_b32_e32 v22, v200, v22, vcc
	v_cmp_le_i32_e32 vcc, v4, v3
	v_or_b32_e32 v4, 41, v208
	s_nop 0
	v_cndmask_b32_e32 v39, v200, v39, vcc
	v_cmp_le_i32_e32 vcc, v4, v3
	v_or_b32_e32 v4, 10, v208
	s_nop 0
	v_cndmask_b32_e32 v23, v200, v23, vcc
	v_cmp_le_i32_e32 vcc, v4, v3
	v_or_b32_e32 v4, 42, v208
	s_nop 0
	v_cndmask_b32_e32 v40, v200, v40, vcc
	v_cmp_le_i32_e32 vcc, v4, v3
	v_or_b32_e32 v4, 11, v208
	s_nop 0
	v_cndmask_b32_e32 v24, v200, v24, vcc
	v_cmp_le_i32_e32 vcc, v4, v3
	v_or_b32_e32 v4, 43, v208
	s_nop 0
	v_cndmask_b32_e32 v41, v200, v41, vcc
	v_cmp_le_i32_e32 vcc, v4, v3
	v_or_b32_e32 v4, 16, v208
	s_nop 0
	v_cndmask_b32_e32 v25, v200, v25, vcc
	v_cmp_le_i32_e32 vcc, v4, v3
	v_or_b32_e32 v4, 48, v208
	s_nop 0
	v_cndmask_b32_e32 v42, v200, v42, vcc
	v_cmp_le_i32_e32 vcc, v4, v3
	v_or_b32_e32 v4, 17, v208
	s_nop 0
	v_cndmask_b32_e32 v26, v200, v26, vcc
	v_cmp_le_i32_e32 vcc, v4, v3
	v_or_b32_e32 v4, 49, v208
	s_nop 0
	v_cndmask_b32_e32 v43, v200, v43, vcc
	v_cmp_le_i32_e32 vcc, v4, v3
	v_or_b32_e32 v4, 18, v208
	s_nop 0
	v_cndmask_b32_e32 v27, v200, v27, vcc
	v_cmp_le_i32_e32 vcc, v4, v3
	v_or_b32_e32 v4, 50, v208
	s_nop 0
	v_cndmask_b32_e32 v44, v200, v44, vcc
	v_cmp_le_i32_e32 vcc, v4, v3
	v_or_b32_e32 v4, 19, v208
	s_nop 0
	v_cndmask_b32_e32 v28, v200, v28, vcc
	v_cmp_le_i32_e32 vcc, v4, v3
	v_or_b32_e32 v4, 51, v208
	s_nop 0
	v_cndmask_b32_e32 v45, v200, v45, vcc
	v_cmp_le_i32_e32 vcc, v4, v3
	v_or_b32_e32 v4, 24, v208
	s_nop 0
	v_cndmask_b32_e32 v29, v200, v29, vcc
	v_cmp_le_i32_e32 vcc, v4, v3
	v_or_b32_e32 v4, 56, v208
	s_nop 0
	v_cndmask_b32_e32 v46, v200, v46, vcc
	v_cmp_le_i32_e32 vcc, v4, v3
	v_or_b32_e32 v4, 25, v208
	s_nop 0
	v_cndmask_b32_e32 v30, v200, v30, vcc
	v_cmp_le_i32_e32 vcc, v4, v3
	v_or_b32_e32 v4, 57, v208
	s_nop 0
	v_cndmask_b32_e32 v47, v200, v47, vcc
	v_cmp_le_i32_e32 vcc, v4, v3
	v_or_b32_e32 v4, 26, v208
	s_nop 0
	v_cndmask_b32_e32 v31, v200, v31, vcc
	v_cmp_le_i32_e32 vcc, v4, v3
	v_or_b32_e32 v4, 58, v208
	s_nop 0
	v_cndmask_b32_e32 v48, v200, v48, vcc
	v_cmp_le_i32_e32 vcc, v4, v3
	v_or_b32_e32 v4, 27, v208
	s_nop 0
	v_cndmask_b32_e32 v32, v200, v32, vcc
	v_cmp_le_i32_e32 vcc, v4, v3
	v_or_b32_e32 v4, 59, v208
	s_nop 0
	v_cndmask_b32_e32 v49, v200, v49, vcc
	v_cmp_le_i32_e32 vcc, v4, v3
	s_nop 1
	v_cndmask_b32_e32 v33, v200, v33, vcc
